# combo6 + LayerNorm loops: gamma/beta loads of the next column block issued before the current block's stores (alternating register sets), counted vmcnt
# baseline (speedup 1.0000x reference)
.LBB0_316:
	v_lshl_add_u64 v[16:17], s[12:13], 0, v[66:67]
	v_add_co_u32_e32 v0, vcc, 0xf8000000, v16
	s_and_b64 s[14:15], s[8:9], exec
	s_nop 0
	v_addc_co_u32_e32 v1, vcc, -1, v17, vcc
	v_add_co_u32_e32 v4, vcc, 0xf8000400, v16
	flat_load_dwordx4 v[0:3], v[0:1]
	s_nop 0
	v_addc_co_u32_e32 v5, vcc, -1, v17, vcc
	flat_load_dwordx4 v[68:71], v[4:5]
	v_add_co_u32_e32 v4, vcc, 0xf8000800, v16
	s_cselect_b32 s15, s18, 0
	s_nop 0
	v_addc_co_u32_e32 v5, vcc, -1, v17, vcc
	flat_load_dwordx4 v[72:75], v[4:5]
	v_add_co_u32_e32 v4, vcc, 0xf8000c00, v16
	s_cselect_b32 s14, s6, 0
	s_nop 0
	v_addc_co_u32_e32 v5, vcc, -1, v17, vcc
	flat_load_dwordx4 v[76:79], v[4:5]
	v_add_co_u32_e32 v4, vcc, 0xf9000000, v16
	v_lshlrev_b32_e32 v176, 2, v52
	s_nop 0
	v_addc_co_u32_e32 v5, vcc, -1, v17, vcc
	flat_load_dwordx4 v[36:39], v[4:5]
	v_add_co_u32_e32 v4, vcc, 0xf9000400, v16
	s_cmp_lg_u64 s[14:15], 0
	s_nop 0
	v_addc_co_u32_e32 v5, vcc, -1, v17, vcc
	flat_load_dwordx4 v[40:43], v[4:5]
	v_add_co_u32_e32 v4, vcc, 0xf9000800, v16
	s_cselect_b64 s[16:17], -1, 0
	s_nop 0
	v_addc_co_u32_e32 v5, vcc, -1, v17, vcc
	flat_load_dwordx4 v[44:47], v[4:5]
	v_add_co_u32_e32 v4, vcc, 0xf9000c00, v16
	s_cmp_eq_u64 s[14:15], 0
	s_nop 0
	v_addc_co_u32_e32 v5, vcc, -1, v17, vcc
	flat_load_dwordx4 v[48:51], v[4:5]
	v_add_co_u32_e32 v4, vcc, 0xfa000000, v16
	s_waitcnt vmcnt(0) lgkmcnt(0)
	v_and_b32_e32 v107, 0xffff0000, v71
	v_lshlrev_b32_e32 v106, 16, v71
	v_and_b32_e32 v111, 0xffff0000, v70
	v_lshlrev_b32_e32 v110, 16, v70
	v_and_b32_e32 v113, 0xffff0000, v69
	v_lshlrev_b32_e32 v112, 16, v69
	v_and_b32_e32 v103, 0xffff0000, v73
	v_lshlrev_b32_e32 v102, 16, v73
	v_and_b32_e32 v105, 0xffff0000, v72
	v_lshlrev_b32_e32 v104, 16, v72
	v_and_b32_e32 v101, 0xffff0000, v74
	v_lshlrev_b32_e32 v100, 16, v74
	v_and_b32_e32 v131, 0xffff0000, v68
	v_lshlrev_b32_e32 v130, 16, v68
	v_addc_co_u32_e32 v5, vcc, -1, v17, vcc
	v_and_b32_e32 v91, 0xffff0000, v79
	v_lshlrev_b32_e32 v90, 16, v79
	v_and_b32_e32 v73, 0xffff0000, v37
	v_lshlrev_b32_e32 v72, 16, v37
	v_and_b32_e32 v37, 0xffff0000, v36
	v_lshlrev_b32_e32 v36, 16, v36
	v_add_f32_e32 v74, 0, v36
	v_add_f32_e32 v74, v74, v37
	v_add_f32_e32 v74, v74, v72
	v_and_b32_e32 v71, 0xffff0000, v39
	v_lshlrev_b32_e32 v70, 16, v39
	v_and_b32_e32 v39, 0xffff0000, v38
	v_lshlrev_b32_e32 v38, 16, v38
	v_add_f32_e32 v74, v74, v73
	v_add_f32_e32 v74, v74, v38
	v_add_f32_e32 v74, v74, v39
	v_add_f32_e32 v74, v74, v70
	v_and_b32_e32 v69, 0xffff0000, v41
	v_lshlrev_b32_e32 v68, 16, v41
	v_and_b32_e32 v41, 0xffff0000, v40
	v_lshlrev_b32_e32 v40, 16, v40
	v_add_f32_e32 v74, v74, v71
	v_add_f32_e32 v74, v74, v40
	v_add_f32_e32 v74, v74, v41
	v_add_f32_e32 v74, v74, v68
	v_and_b32_e32 v93, 0xffff0000, v78
	v_lshlrev_b32_e32 v92, 16, v78
	v_and_b32_e32 v79, 0xffff0000, v49
	v_lshlrev_b32_e32 v78, 16, v49
	v_and_b32_e32 v83, 0xffff0000, v48
	v_lshlrev_b32_e32 v82, 16, v48
	v_and_b32_e32 v49, 0xffff0000, v47
	v_lshlrev_b32_e32 v48, 16, v47
	v_and_b32_e32 v85, 0xffff0000, v46
	v_lshlrev_b32_e32 v84, 16, v46
	v_and_b32_e32 v47, 0xffff0000, v43
	v_lshlrev_b32_e32 v46, 16, v43
	v_and_b32_e32 v43, 0xffff0000, v42
	v_lshlrev_b32_e32 v42, 16, v42
	v_add_f32_e32 v74, v74, v69
	flat_load_dwordx4 v[20:23], v[4:5]
	v_add_f32_e32 v74, v74, v42
	v_add_f32_e32 v74, v74, v43
	v_add_f32_e32 v74, v74, v46
	v_and_b32_e32 v95, 0xffff0000, v77
	v_lshlrev_b32_e32 v94, 16, v77
	v_and_b32_e32 v97, 0xffff0000, v76
	v_lshlrev_b32_e32 v96, 16, v76
	v_and_b32_e32 v77, 0xffff0000, v51
	v_lshlrev_b32_e32 v76, 16, v51
	v_and_b32_e32 v81, 0xffff0000, v50
	v_lshlrev_b32_e32 v80, 16, v50
	v_and_b32_e32 v51, 0xffff0000, v45
	v_lshlrev_b32_e32 v50, 16, v45
	v_and_b32_e32 v45, 0xffff0000, v44
	v_lshlrev_b32_e32 v44, 16, v44
	v_add_f32_e32 v74, v74, v47
	v_add_f32_e32 v74, v74, v44
	v_add_f32_e32 v74, v74, v45
	v_add_co_u32_e32 v4, vcc, 0xfa000400, v16
	v_add_f32_e32 v74, v74, v50
	s_nop 0
	v_addc_co_u32_e32 v5, vcc, -1, v17, vcc
	v_add_f32_e32 v74, v74, v51
	flat_load_dwordx4 v[24:27], v[4:5]
	v_add_co_u32_e32 v4, vcc, 0xfa000800, v16
	v_add_f32_e32 v74, v74, v84
	s_nop 0
	v_addc_co_u32_e32 v5, vcc, -1, v17, vcc
	v_add_f32_e32 v74, v74, v85
	flat_load_dwordx4 v[28:31], v[4:5]
	v_add_co_u32_e32 v4, vcc, 0xfa000c00, v16
	v_add_f32_e32 v74, v74, v48
	s_nop 0
	v_addc_co_u32_e32 v5, vcc, -1, v17, vcc
	v_add_f32_e32 v74, v74, v49
	flat_load_dwordx4 v[32:35], v[4:5]
	v_add_f32_e32 v74, v74, v82
	v_add_f32_e32 v74, v74, v83
	v_add_f32_e32 v74, v74, v78
	v_add_f32_e32 v74, v74, v79
	v_add_f32_e32 v74, v74, v80
	v_add_f32_e32 v74, v74, v81
	v_add_f32_e32 v74, v74, v76
	v_add_f32_e32 v74, v74, v77
	v_and_b32_e32 v99, 0xffff0000, v75
	v_lshlrev_b32_e32 v98, 16, v75
	ds_bpermute_b32 v75, v53, v74
	v_add_co_u32_e32 v4, vcc, 0xfb000000, v16
	s_waitcnt lgkmcnt(0)
	v_add_f32_e32 v74, v74, v75
	ds_bpermute_b32 v75, v171, v74
	v_addc_co_u32_e32 v5, vcc, -1, v17, vcc
	flat_load_dwordx4 v[4:7], v[4:5]
	v_add_co_u32_e32 v8, vcc, 0xfb000400, v16
	s_waitcnt lgkmcnt(0)
	v_add_f32_e32 v74, v74, v75
	ds_bpermute_b32 v75, v172, v74
	v_addc_co_u32_e32 v9, vcc, -1, v17, vcc
	flat_load_dwordx4 v[8:11], v[8:9]
	v_add_co_u32_e32 v12, vcc, 0xfb000800, v16
	s_waitcnt lgkmcnt(0)
	v_add_f32_e32 v74, v74, v75
	ds_bpermute_b32 v75, v173, v74
	v_addc_co_u32_e32 v13, vcc, -1, v17, vcc
	flat_load_dwordx4 v[12:15], v[12:13]
	v_add_co_u32_e32 v16, vcc, 0xfb000c00, v16
	s_waitcnt lgkmcnt(0)
	v_add_f32_e32 v74, v74, v75
	ds_bpermute_b32 v75, v174, v74
	v_addc_co_u32_e32 v17, vcc, -1, v17, vcc
	flat_load_dwordx4 v[16:19], v[16:17]
	s_waitcnt lgkmcnt(0)
	v_add_f32_e32 v74, v74, v75
	ds_bpermute_b32 v75, v175, v74
	s_waitcnt lgkmcnt(0)
	v_add_f32_e32 v74, v74, v75
	v_mul_f32_e32 v86, 0x3a000000, v74
	v_pk_add_f32 v[114:115], v[36:37], v[86:87] op_sel_hi:[1,0] neg_lo:[0,1] neg_hi:[0,1]
	v_pk_add_f32 v[108:109], v[72:73], v[86:87] op_sel_hi:[1,0] neg_lo:[0,1] neg_hi:[0,1]
	v_pk_mul_f32 v[88:89], v[114:115], v[114:115]
	v_pk_mul_f32 v[118:119], v[108:109], v[108:109]
	v_pk_add_f32 v[120:121], v[38:39], v[86:87] op_sel_hi:[1,0] neg_lo:[0,1] neg_hi:[0,1]
	v_pk_add_f32 v[116:117], v[70:71], v[86:87] op_sel_hi:[1,0] neg_lo:[0,1] neg_hi:[0,1]
	v_pk_add_f32 v[70:71], v[40:41], v[86:87] op_sel_hi:[1,0] neg_lo:[0,1] neg_hi:[0,1]
	v_pk_add_f32 v[68:69], v[68:69], v[86:87] op_sel_hi:[1,0] neg_lo:[0,1] neg_hi:[0,1]
	v_pk_add_f32 v[74:75], v[42:43], v[86:87] op_sel_hi:[1,0] neg_lo:[0,1] neg_hi:[0,1]
	v_pk_add_f32 v[72:73], v[46:47], v[86:87] op_sel_hi:[1,0] neg_lo:[0,1] neg_hi:[0,1]
	v_pk_add_f32 v[46:47], v[44:45], v[86:87] op_sel_hi:[1,0] neg_lo:[0,1] neg_hi:[0,1]
	v_pk_add_f32 v[44:45], v[50:51], v[86:87] op_sel_hi:[1,0] neg_lo:[0,1] neg_hi:[0,1]
	v_pk_add_f32 v[50:51], v[84:85], v[86:87] op_sel_hi:[1,0] neg_lo:[0,1] neg_hi:[0,1]
	v_pk_add_f32 v[48:49], v[48:49], v[86:87] op_sel_hi:[1,0] neg_lo:[0,1] neg_hi:[0,1]
	v_pk_add_f32 v[38:39], v[82:83], v[86:87] op_sel_hi:[1,0] neg_lo:[0,1] neg_hi:[0,1]
	v_pk_add_f32 v[36:37], v[78:79], v[86:87] op_sel_hi:[1,0] neg_lo:[0,1] neg_hi:[0,1]
	v_pk_add_f32 v[42:43], v[80:81], v[86:87] op_sel_hi:[1,0] neg_lo:[0,1] neg_hi:[0,1]
	v_pk_add_f32 v[40:41], v[76:77], v[86:87] op_sel_hi:[1,0] neg_lo:[0,1] neg_hi:[0,1]
	v_add_f32_e32 v86, v88, v89
	v_add_f32_e32 v86, v118, v86
	v_pk_mul_f32 v[122:123], v[120:121], v[120:121]
	v_add_f32_e32 v86, v119, v86
	v_add_f32_e32 v86, v122, v86
	v_pk_mul_f32 v[124:125], v[116:117], v[116:117]
	v_add_f32_e32 v86, v123, v86
	v_add_f32_e32 v86, v124, v86
	v_pk_mul_f32 v[126:127], v[70:71], v[70:71]
	v_add_f32_e32 v86, v125, v86
	v_add_f32_e32 v86, v126, v86
	v_pk_mul_f32 v[132:133], v[68:69], v[68:69]
	v_add_f32_e32 v86, v127, v86
	v_add_f32_e32 v86, v132, v86
	v_pk_mul_f32 v[134:135], v[74:75], v[74:75]
	v_add_f32_e32 v86, v133, v86
	v_add_f32_e32 v86, v134, v86
	v_pk_mul_f32 v[136:137], v[72:73], v[72:73]
	v_add_f32_e32 v86, v135, v86
	v_add_f32_e32 v86, v136, v86
	v_pk_mul_f32 v[138:139], v[46:47], v[46:47]
	v_add_f32_e32 v86, v137, v86
	v_add_f32_e32 v86, v138, v86
	v_pk_mul_f32 v[140:141], v[44:45], v[44:45]
	v_add_f32_e32 v86, v139, v86
	v_add_f32_e32 v86, v140, v86
	v_pk_mul_f32 v[84:85], v[50:51], v[50:51]
	v_add_f32_e32 v86, v141, v86
	v_add_f32_e32 v84, v84, v86
	v_pk_mul_f32 v[142:143], v[48:49], v[48:49]
	v_add_f32_e32 v84, v85, v84
	v_add_f32_e32 v84, v142, v84
	s_waitcnt vmcnt(0)
	v_and_b32_e32 v123, 0xffff0000, v21
	v_lshlrev_b32_e32 v122, 16, v21
	v_and_b32_e32 v21, 0xffff0000, v20
	v_lshlrev_b32_e32 v20, 16, v20
	v_pk_mul_f32 v[82:83], v[38:39], v[38:39]
	v_add_f32_e32 v84, v143, v84
	v_add_f32_e32 v89, 0, v20
	v_add_f32_e32 v82, v82, v84
	v_add_f32_e32 v89, v89, v21
	v_pk_mul_f32 v[78:79], v[36:37], v[36:37]
	v_add_f32_e32 v82, v83, v82
	v_add_f32_e32 v89, v89, v122
	v_add_f32_e32 v78, v78, v82
	v_and_b32_e32 v119, 0xffff0000, v23
	v_lshlrev_b32_e32 v118, 16, v23
	v_and_b32_e32 v23, 0xffff0000, v22
	v_lshlrev_b32_e32 v22, 16, v22
	v_add_f32_e32 v89, v89, v123
	v_pk_mul_f32 v[80:81], v[42:43], v[42:43]
	v_add_f32_e32 v78, v79, v78
	v_add_f32_e32 v89, v89, v22
	v_add_f32_e32 v78, v80, v78
	v_add_f32_e32 v89, v89, v23
	v_pk_mul_f32 v[76:77], v[40:41], v[40:41]
	v_add_f32_e32 v78, v81, v78
	v_add_f32_e32 v89, v89, v118
	v_add_f32_e32 v76, v76, v78
	v_and_b32_e32 v79, 0xffff0000, v25
	v_lshlrev_b32_e32 v78, 16, v25
	v_and_b32_e32 v25, 0xffff0000, v24
	v_lshlrev_b32_e32 v24, 16, v24
	v_add_f32_e32 v89, v89, v119
	v_add_f32_e32 v89, v89, v24
	v_add_f32_e32 v89, v89, v25
	v_add_f32_e32 v89, v89, v78
	v_and_b32_e32 v81, 0xffff0000, v35
	v_lshlrev_b32_e32 v80, 16, v35
	v_and_b32_e32 v85, 0xffff0000, v34
	v_lshlrev_b32_e32 v84, 16, v34
	v_and_b32_e32 v35, 0xffff0000, v27
	v_lshlrev_b32_e32 v34, 16, v27
	v_and_b32_e32 v27, 0xffff0000, v26
	v_lshlrev_b32_e32 v26, 16, v26
	v_add_f32_e32 v89, v89, v79
	v_add_f32_e32 v89, v89, v26
	v_add_f32_e32 v89, v89, v27
	v_add_f32_e32 v89, v89, v34
	v_and_b32_e32 v83, 0xffff0000, v33
	v_lshlrev_b32_e32 v82, 16, v33
	v_and_b32_e32 v87, 0xffff0000, v32
	v_lshlrev_b32_e32 v86, 16, v32
	v_and_b32_e32 v33, 0xffff0000, v29
	v_lshlrev_b32_e32 v32, 16, v29
	v_and_b32_e32 v29, 0xffff0000, v28
	v_lshlrev_b32_e32 v28, 16, v28
	v_add_f32_e32 v89, v89, v35
	v_add_f32_e32 v89, v89, v28
	v_add_f32_e32 v89, v89, v29
	v_add_f32_e32 v89, v89, v32
	v_add_f32_e32 v88, v77, v76
	v_and_b32_e32 v77, 0xffff0000, v31
	v_lshlrev_b32_e32 v76, 16, v31
	v_and_b32_e32 v31, 0xffff0000, v30
	v_lshlrev_b32_e32 v30, 16, v30
	v_add_f32_e32 v89, v89, v33
	v_add_f32_e32 v89, v89, v30
	v_add_f32_e32 v89, v89, v31
	v_add_f32_e32 v89, v89, v76
	v_add_f32_e32 v89, v89, v77
	v_add_f32_e32 v89, v89, v86
	v_add_f32_e32 v89, v89, v87
	v_add_f32_e32 v89, v89, v82
	v_add_f32_e32 v89, v89, v83
	v_add_f32_e32 v89, v89, v84
	v_add_f32_e32 v89, v89, v85
	v_add_f32_e32 v89, v89, v80
	v_add_f32_e32 v89, v89, v81
	ds_bpermute_b32 v124, v53, v89
	s_waitcnt lgkmcnt(0)
	v_add_f32_e32 v89, v89, v124
	ds_bpermute_b32 v124, v171, v89
	s_waitcnt lgkmcnt(0)
	v_add_f32_e32 v89, v89, v124
	ds_bpermute_b32 v124, v172, v89
	s_waitcnt lgkmcnt(0)
	v_add_f32_e32 v89, v89, v124
	ds_bpermute_b32 v124, v173, v89
	s_waitcnt lgkmcnt(0)
	v_add_f32_e32 v89, v89, v124
	ds_bpermute_b32 v124, v174, v89
	s_waitcnt lgkmcnt(0)
	v_add_f32_e32 v89, v89, v124
	ds_bpermute_b32 v124, v175, v89
	s_waitcnt lgkmcnt(0)
	v_add_f32_e32 v89, v89, v124
	v_mul_f32_e32 v132, 0x3a000000, v89
	v_pk_add_f32 v[142:143], v[20:21], v[132:133] op_sel_hi:[1,0] neg_lo:[0,1] neg_hi:[0,1]
	v_pk_add_f32 v[140:141], v[122:123], v[132:133] op_sel_hi:[1,0] neg_lo:[0,1] neg_hi:[0,1]
	v_pk_mul_f32 v[20:21], v[142:143], v[142:143]
	v_pk_mul_f32 v[134:135], v[140:141], v[140:141]
	v_add_f32_e32 v20, v20, v21
	v_pk_add_f32 v[146:147], v[22:23], v[132:133] op_sel_hi:[1,0] neg_lo:[0,1] neg_hi:[0,1]
	v_add_f32_e32 v20, v134, v20
	v_pk_mul_f32 v[22:23], v[146:147], v[146:147]
	v_add_f32_e32 v20, v135, v20
	v_pk_add_f32 v[144:145], v[118:119], v[132:133] op_sel_hi:[1,0] neg_lo:[0,1] neg_hi:[0,1]
	v_add_f32_e32 v20, v22, v20
	v_pk_mul_f32 v[136:137], v[144:145], v[144:145]
	v_add_f32_e32 v20, v23, v20
	v_pk_add_f32 v[122:123], v[24:25], v[132:133] op_sel_hi:[1,0] neg_lo:[0,1] neg_hi:[0,1]
	v_add_f32_e32 v20, v136, v20
	v_pk_mul_f32 v[138:139], v[122:123], v[122:123]
	v_add_f32_e32 v20, v137, v20
	v_pk_add_f32 v[118:119], v[78:79], v[132:133] op_sel_hi:[1,0] neg_lo:[0,1] neg_hi:[0,1]
	v_add_f32_e32 v20, v138, v20
	v_pk_mul_f32 v[148:149], v[118:119], v[118:119]
	v_add_f32_e32 v20, v139, v20
	v_pk_add_f32 v[126:127], v[26:27], v[132:133] op_sel_hi:[1,0] neg_lo:[0,1] neg_hi:[0,1]
	v_add_f32_e32 v20, v148, v20
	v_pk_mul_f32 v[150:151], v[126:127], v[126:127]
	v_add_f32_e32 v20, v149, v20
	v_pk_add_f32 v[124:125], v[34:35], v[132:133] op_sel_hi:[1,0] neg_lo:[0,1] neg_hi:[0,1]
	v_add_f32_e32 v20, v150, v20
	v_pk_mul_f32 v[152:153], v[124:125], v[124:125]
	v_add_f32_e32 v20, v151, v20
	v_pk_add_f32 v[34:35], v[28:29], v[132:133] op_sel_hi:[1,0] neg_lo:[0,1] neg_hi:[0,1]
	v_add_f32_e32 v20, v152, v20
	v_pk_mul_f32 v[154:155], v[34:35], v[34:35]
	v_add_f32_e32 v20, v153, v20
	v_pk_add_f32 v[32:33], v[32:33], v[132:133] op_sel_hi:[1,0] neg_lo:[0,1] neg_hi:[0,1]
	v_add_f32_e32 v20, v154, v20
	v_pk_mul_f32 v[156:157], v[32:33], v[32:33]
	v_add_f32_e32 v20, v155, v20
	v_and_b32_e32 v135, 0xffff0000, v5
	v_lshlrev_b32_e32 v134, 16, v5
	v_and_b32_e32 v5, 0xffff0000, v4
	v_lshlrev_b32_e32 v4, 16, v4
	v_pk_add_f32 v[78:79], v[30:31], v[132:133] op_sel_hi:[1,0] neg_lo:[0,1] neg_hi:[0,1]
	v_add_f32_e32 v20, v156, v20
	v_add_f32_e32 v136, 0, v4
	v_pk_mul_f32 v[158:159], v[78:79], v[78:79]
	v_add_f32_e32 v20, v157, v20
	v_add_f32_e32 v136, v136, v5
	v_pk_add_f32 v[76:77], v[76:77], v[132:133] op_sel_hi:[1,0] neg_lo:[0,1] neg_hi:[0,1]
	v_add_f32_e32 v20, v158, v20
	v_add_f32_e32 v136, v136, v134
	v_pk_mul_f32 v[160:161], v[76:77], v[76:77]
	v_pk_add_f32 v[26:27], v[86:87], v[132:133] op_sel_hi:[1,0] neg_lo:[0,1] neg_hi:[0,1]
	v_pk_add_f32 v[24:25], v[82:83], v[132:133] op_sel_hi:[1,0] neg_lo:[0,1] neg_hi:[0,1]
	v_pk_add_f32 v[30:31], v[84:85], v[132:133] op_sel_hi:[1,0] neg_lo:[0,1] neg_hi:[0,1]
	v_pk_add_f32 v[28:29], v[80:81], v[132:133] op_sel_hi:[1,0] neg_lo:[0,1] neg_hi:[0,1]
	v_add_f32_e32 v20, v159, v20
	v_and_b32_e32 v133, 0xffff0000, v7
	v_lshlrev_b32_e32 v132, 16, v7
	v_and_b32_e32 v7, 0xffff0000, v6
	v_lshlrev_b32_e32 v6, 16, v6
	v_add_f32_e32 v136, v136, v135
	v_add_f32_e32 v20, v160, v20
	v_add_f32_e32 v136, v136, v6
	v_pk_mul_f32 v[86:87], v[26:27], v[26:27]
	v_add_f32_e32 v20, v161, v20
	v_add_f32_e32 v136, v136, v7
	v_add_f32_e32 v20, v86, v20
	v_add_f32_e32 v136, v136, v132
	v_pk_mul_f32 v[82:83], v[24:25], v[24:25]
	v_add_f32_e32 v20, v87, v20
	v_and_b32_e32 v87, 0xffff0000, v9
	v_lshlrev_b32_e32 v86, 16, v9
	v_and_b32_e32 v9, 0xffff0000, v8
	v_lshlrev_b32_e32 v8, 16, v8
	v_add_f32_e32 v136, v136, v133
	v_add_f32_e32 v20, v82, v20
	v_add_f32_e32 v136, v136, v8
	v_pk_mul_f32 v[84:85], v[30:31], v[30:31]
	v_add_f32_e32 v20, v83, v20
	v_add_f32_e32 v136, v136, v9
	v_add_f32_e32 v20, v84, v20
	v_add_f32_e32 v136, v136, v86
	v_add_f32_e32 v20, v85, v20
	v_and_b32_e32 v85, 0xffff0000, v11
	v_lshlrev_b32_e32 v84, 16, v11
	v_and_b32_e32 v11, 0xffff0000, v10
	v_lshlrev_b32_e32 v10, 16, v10
	v_add_f32_e32 v136, v136, v87
	v_add_f32_e32 v136, v136, v10
	v_add_f32_e32 v136, v136, v11
	v_add_f32_e32 v136, v136, v84
	v_and_b32_e32 v83, 0xffff0000, v13
	v_lshlrev_b32_e32 v82, 16, v13
	v_and_b32_e32 v13, 0xffff0000, v12
	v_lshlrev_b32_e32 v12, 16, v12
	v_add_f32_e32 v136, v136, v85
	v_add_f32_e32 v136, v136, v12
	v_pk_mul_f32 v[80:81], v[28:29], v[28:29]
	v_add_f32_e32 v136, v136, v13
	v_add_f32_e32 v20, v80, v20
	v_add_f32_e32 v136, v136, v82
	v_add_f32_e32 v89, v81, v20
	v_and_b32_e32 v81, 0xffff0000, v15
	v_lshlrev_b32_e32 v80, 16, v15
	v_and_b32_e32 v15, 0xffff0000, v14
	v_lshlrev_b32_e32 v14, 16, v14
	v_add_f32_e32 v136, v136, v83
	v_add_f32_e32 v136, v136, v14
	v_add_f32_e32 v136, v136, v15
	v_add_f32_e32 v136, v136, v80
	v_and_b32_e32 v23, 0xffff0000, v17
	v_lshlrev_b32_e32 v22, 16, v17
	v_and_b32_e32 v17, 0xffff0000, v16
	v_lshlrev_b32_e32 v16, 16, v16
	v_add_f32_e32 v136, v136, v81
	v_add_f32_e32 v136, v136, v16
	v_add_f32_e32 v136, v136, v17
	v_add_f32_e32 v136, v136, v22
	v_and_b32_e32 v21, 0xffff0000, v19
	v_lshlrev_b32_e32 v20, 16, v19
	v_and_b32_e32 v19, 0xffff0000, v18
	v_lshlrev_b32_e32 v18, 16, v18
	v_add_f32_e32 v136, v136, v23
	v_add_f32_e32 v136, v136, v18
	v_add_f32_e32 v136, v136, v19
	v_add_f32_e32 v136, v136, v20
	v_add_f32_e32 v136, v136, v21
	ds_bpermute_b32 v137, v53, v136
	s_waitcnt lgkmcnt(0)
	v_add_f32_e32 v136, v136, v137
	ds_bpermute_b32 v137, v171, v136
	s_waitcnt lgkmcnt(0)
	v_add_f32_e32 v136, v136, v137
	ds_bpermute_b32 v137, v172, v136
	s_waitcnt lgkmcnt(0)
	v_add_f32_e32 v136, v136, v137
	ds_bpermute_b32 v137, v173, v136
	s_waitcnt lgkmcnt(0)
	v_add_f32_e32 v136, v136, v137
	ds_bpermute_b32 v137, v174, v136
	s_waitcnt lgkmcnt(0)
	v_add_f32_e32 v136, v136, v137
	ds_bpermute_b32 v137, v175, v136
	s_waitcnt lgkmcnt(0)
	v_add_f32_e32 v136, v136, v137
	v_mul_f32_e32 v164, 0x3a000000, v136
	v_pk_add_f32 v[158:159], v[4:5], v[164:165] op_sel_hi:[1,0] neg_lo:[0,1] neg_hi:[0,1]
	v_pk_add_f32 v[156:157], v[134:135], v[164:165] op_sel_hi:[1,0] neg_lo:[0,1] neg_hi:[0,1]
	v_pk_mul_f32 v[4:5], v[158:159], v[158:159]
	v_pk_mul_f32 v[166:167], v[156:157], v[156:157]
	v_add_f32_e32 v4, v4, v5
	v_pk_add_f32 v[162:163], v[6:7], v[164:165] op_sel_hi:[1,0] neg_lo:[0,1] neg_hi:[0,1]
	v_add_f32_e32 v4, v166, v4
	v_pk_mul_f32 v[6:7], v[162:163], v[162:163]
	v_add_f32_e32 v4, v167, v4
	v_pk_add_f32 v[160:161], v[132:133], v[164:165] op_sel_hi:[1,0] neg_lo:[0,1] neg_hi:[0,1]
	v_add_f32_e32 v4, v6, v4
	v_pk_mul_f32 v[168:169], v[160:161], v[160:161]
	v_add_f32_e32 v4, v7, v4
	v_pk_add_f32 v[150:151], v[8:9], v[164:165] op_sel_hi:[1,0] neg_lo:[0,1] neg_hi:[0,1]
	v_add_f32_e32 v4, v168, v4
	v_pk_mul_f32 v[8:9], v[150:151], v[150:151]
	v_add_f32_e32 v4, v169, v4
	v_pk_add_f32 v[148:149], v[86:87], v[164:165] op_sel_hi:[1,0] neg_lo:[0,1] neg_hi:[0,1]
	v_add_f32_e32 v4, v8, v4
	v_pk_mul_f32 v[180:181], v[148:149], v[148:149]
	v_add_f32_e32 v4, v9, v4
	v_pk_add_f32 v[154:155], v[10:11], v[164:165] op_sel_hi:[1,0] neg_lo:[0,1] neg_hi:[0,1]
	v_add_f32_e32 v4, v180, v4
	v_pk_mul_f32 v[10:11], v[154:155], v[154:155]
	v_add_f32_e32 v4, v181, v4
	v_pk_add_f32 v[152:153], v[84:85], v[164:165] op_sel_hi:[1,0] neg_lo:[0,1] neg_hi:[0,1]
	v_add_f32_e32 v4, v10, v4
	v_pk_mul_f32 v[182:183], v[152:153], v[152:153]
	v_add_f32_e32 v4, v11, v4
	v_pk_add_f32 v[134:135], v[12:13], v[164:165] op_sel_hi:[1,0] neg_lo:[0,1] neg_hi:[0,1]
	v_add_f32_e32 v4, v182, v4
	v_pk_mul_f32 v[12:13], v[134:135], v[134:135]
	v_add_f32_e32 v4, v183, v4
	v_pk_add_f32 v[132:133], v[82:83], v[164:165] op_sel_hi:[1,0] neg_lo:[0,1] neg_hi:[0,1]
	v_add_f32_e32 v4, v12, v4
	v_pk_mul_f32 v[184:185], v[132:133], v[132:133]
	v_add_f32_e32 v4, v13, v4
	v_pk_add_f32 v[138:139], v[14:15], v[164:165] op_sel_hi:[1,0] neg_lo:[0,1] neg_hi:[0,1]
	v_add_f32_e32 v4, v184, v4
	v_pk_mul_f32 v[14:15], v[138:139], v[138:139]
	v_add_f32_e32 v4, v185, v4
	v_pk_add_f32 v[136:137], v[80:81], v[164:165] op_sel_hi:[1,0] neg_lo:[0,1] neg_hi:[0,1]
	v_add_f32_e32 v4, v14, v4
	v_pk_mul_f32 v[186:187], v[136:137], v[136:137]
	v_add_f32_e32 v4, v15, v4
	v_pk_add_f32 v[82:83], v[16:17], v[164:165] op_sel_hi:[1,0] neg_lo:[0,1] neg_hi:[0,1]
	v_add_f32_e32 v4, v186, v4
	v_pk_mul_f32 v[16:17], v[82:83], v[82:83]
	v_add_f32_e32 v4, v187, v4
	v_pk_add_f32 v[80:81], v[22:23], v[164:165] op_sel_hi:[1,0] neg_lo:[0,1] neg_hi:[0,1]
	v_add_f32_e32 v4, v16, v4
	v_pk_mul_f32 v[22:23], v[80:81], v[80:81]
	v_add_f32_e32 v4, v17, v4
	v_pk_add_f32 v[86:87], v[18:19], v[164:165] op_sel_hi:[1,0] neg_lo:[0,1] neg_hi:[0,1]
	v_add_f32_e32 v4, v22, v4
	v_pk_mul_f32 v[18:19], v[86:87], v[86:87]
	v_add_f32_e32 v4, v23, v4
	v_and_b32_e32 v23, 0xffff0000, v1
	v_lshlrev_b32_e32 v22, 16, v1
	v_and_b32_e32 v1, 0xffff0000, v0
	v_lshlrev_b32_e32 v0, 16, v0
	v_pk_add_f32 v[84:85], v[20:21], v[164:165] op_sel_hi:[1,0] neg_lo:[0,1] neg_hi:[0,1]
	v_add_f32_e32 v4, v18, v4
	v_add_f32_e32 v164, 0, v0
	v_pk_mul_f32 v[20:21], v[84:85], v[84:85]
	v_add_f32_e32 v4, v19, v4
	v_add_f32_e32 v164, v164, v1
	v_add_f32_e32 v4, v20, v4
	v_add_f32_e32 v164, v164, v22
	v_add_f32_e32 v4, v21, v4
	v_and_b32_e32 v21, 0xffff0000, v3
	v_lshlrev_b32_e32 v20, 16, v3
	v_and_b32_e32 v3, 0xffff0000, v2
	v_lshlrev_b32_e32 v2, 16, v2
	v_add_f32_e32 v164, v164, v23
	v_add_f32_e32 v164, v164, v2
	v_add_f32_e32 v164, v164, v3
	v_add_f32_e32 v164, v164, v20
	v_add_f32_e32 v164, v164, v21
	v_add_f32_e32 v164, v164, v130
	v_add_f32_e32 v164, v164, v131
	v_add_f32_e32 v164, v164, v112
	v_add_f32_e32 v164, v164, v113
	v_add_f32_e32 v164, v164, v110
	v_add_f32_e32 v164, v164, v111
	v_add_f32_e32 v164, v164, v106
	v_add_f32_e32 v164, v164, v107
	v_add_f32_e32 v164, v164, v104
	v_add_f32_e32 v164, v164, v105
	v_add_f32_e32 v164, v164, v102
	v_add_f32_e32 v164, v164, v103
	v_add_f32_e32 v164, v164, v100
	v_add_f32_e32 v164, v164, v101
	v_add_f32_e32 v164, v164, v98
	ds_bpermute_b32 v5, v53, v88
	v_add_f32_e32 v164, v164, v99
	ds_bpermute_b32 v7, v53, v4
	v_add_f32_e32 v164, v164, v96
	v_add_f32_e32 v164, v164, v97
	v_add_f32_e32 v164, v164, v94
	v_add_f32_e32 v164, v164, v95
	s_waitcnt lgkmcnt(1)
	v_add_f32_e32 v5, v88, v5
	ds_bpermute_b32 v6, v53, v89
	v_add_f32_e32 v164, v164, v92
	s_waitcnt lgkmcnt(1)
	v_add_f32_e32 v4, v4, v7
	ds_bpermute_b32 v7, v171, v5
	v_add_f32_e32 v164, v164, v93
	v_add_f32_e32 v164, v164, v90
	v_add_f32_e32 v164, v164, v91
	ds_bpermute_b32 v165, v53, v164
	s_waitcnt lgkmcnt(2)
	v_add_f32_e32 v6, v89, v6
	s_waitcnt lgkmcnt(1)
	v_add_f32_e32 v5, v5, v7
	ds_bpermute_b32 v7, v171, v6
	v_lshl_add_u64 v[88:89], s[14:15], 0, v[176:177]
	s_waitcnt lgkmcnt(1)
	v_add_f32_e32 v164, v164, v165
	ds_bpermute_b32 v165, v171, v164
	s_waitcnt lgkmcnt(1)
	v_add_f32_e32 v6, v6, v7
	ds_bpermute_b32 v7, v171, v4
	s_waitcnt lgkmcnt(1)
	v_add_f32_e32 v164, v164, v165
	ds_bpermute_b32 v165, v172, v164
	s_waitcnt lgkmcnt(1)
	v_add_f32_e32 v4, v4, v7
	ds_bpermute_b32 v7, v172, v5
	s_waitcnt lgkmcnt(1)
	v_add_f32_e32 v164, v164, v165
	ds_bpermute_b32 v165, v173, v164
	s_waitcnt lgkmcnt(1)
	v_add_f32_e32 v5, v5, v7
	ds_bpermute_b32 v7, v172, v6
	s_waitcnt lgkmcnt(1)
	v_add_f32_e32 v164, v164, v165
	ds_bpermute_b32 v165, v174, v164
	s_waitcnt lgkmcnt(1)
	v_add_f32_e32 v6, v6, v7
	ds_bpermute_b32 v7, v172, v4
	s_waitcnt lgkmcnt(1)
	v_add_f32_e32 v164, v164, v165
	ds_bpermute_b32 v165, v175, v164
	s_waitcnt lgkmcnt(1)
	v_add_f32_e32 v4, v4, v7
	ds_bpermute_b32 v7, v173, v5
	s_waitcnt lgkmcnt(1)
	v_add_f32_e32 v164, v164, v165
	v_mul_f32_e32 v176, 0x3a000000, v164
	v_pk_add_f32 v[0:1], v[0:1], v[176:177] op_sel_hi:[1,0] neg_lo:[0,1] neg_hi:[0,1]
	s_waitcnt lgkmcnt(0)
	v_add_f32_e32 v5, v5, v7
	ds_bpermute_b32 v7, v173, v6
	v_pk_mul_f32 v[186:187], v[0:1], v[0:1]
	v_pk_add_f32 v[22:23], v[22:23], v[176:177] op_sel_hi:[1,0] neg_lo:[0,1] neg_hi:[0,1]
	v_pk_add_f32 v[2:3], v[2:3], v[176:177] op_sel_hi:[1,0] neg_lo:[0,1] neg_hi:[0,1]
	v_pk_mul_f32 v[188:189], v[22:23], v[22:23]
	s_waitcnt lgkmcnt(0)
	v_add_f32_e32 v6, v6, v7
	ds_bpermute_b32 v7, v173, v4
	v_pk_add_f32 v[192:193], v[20:21], v[176:177] op_sel_hi:[1,0] neg_lo:[0,1] neg_hi:[0,1]
	v_pk_add_f32 v[130:131], v[130:131], v[176:177] op_sel_hi:[1,0] neg_lo:[0,1] neg_hi:[0,1]
	v_pk_add_f32 v[164:165], v[112:113], v[176:177] op_sel_hi:[1,0] neg_lo:[0,1] neg_hi:[0,1]
	v_pk_add_f32 v[166:167], v[110:111], v[176:177] op_sel_hi:[1,0] neg_lo:[0,1] neg_hi:[0,1]
	v_pk_add_f32 v[168:169], v[106:107], v[176:177] op_sel_hi:[1,0] neg_lo:[0,1] neg_hi:[0,1]
	v_pk_add_f32 v[104:105], v[104:105], v[176:177] op_sel_hi:[1,0] neg_lo:[0,1] neg_hi:[0,1]
	v_pk_add_f32 v[102:103], v[102:103], v[176:177] op_sel_hi:[1,0] neg_lo:[0,1] neg_hi:[0,1]
	v_pk_add_f32 v[110:111], v[100:101], v[176:177] op_sel_hi:[1,0] neg_lo:[0,1] neg_hi:[0,1]
	v_pk_add_f32 v[106:107], v[98:99], v[176:177] op_sel_hi:[1,0] neg_lo:[0,1] neg_hi:[0,1]
	v_pk_add_f32 v[96:97], v[96:97], v[176:177] op_sel_hi:[1,0] neg_lo:[0,1] neg_hi:[0,1]
	v_pk_add_f32 v[94:95], v[94:95], v[176:177] op_sel_hi:[1,0] neg_lo:[0,1] neg_hi:[0,1]
	v_pk_add_f32 v[92:93], v[92:93], v[176:177] op_sel_hi:[1,0] neg_lo:[0,1] neg_hi:[0,1]
	v_pk_add_f32 v[90:91], v[90:91], v[176:177] op_sel_hi:[1,0] neg_lo:[0,1] neg_hi:[0,1]
	v_add_f32_e32 v176, v186, v187
	v_add_f32_e32 v176, v188, v176
	v_pk_mul_f32 v[190:191], v[2:3], v[2:3]
	v_add_f32_e32 v176, v189, v176
	s_waitcnt lgkmcnt(0)
	v_add_f32_e32 v4, v4, v7
	ds_bpermute_b32 v7, v174, v5
	v_add_f32_e32 v176, v190, v176
	v_pk_mul_f32 v[20:21], v[192:193], v[192:193]
	v_add_f32_e32 v176, v191, v176
	v_add_f32_e32 v20, v20, v176
	v_pk_mul_f32 v[194:195], v[130:131], v[130:131]
	v_add_f32_e32 v20, v21, v20
	v_add_f32_e32 v20, v194, v20
	s_waitcnt lgkmcnt(0)
	v_add_f32_e32 v184, v5, v7
	ds_bpermute_b32 v5, v174, v6
	v_pk_mul_f32 v[112:113], v[164:165], v[164:165]
	v_add_f32_e32 v20, v195, v20
	v_add_f32_e32 v20, v112, v20
	v_pk_mul_f32 v[196:197], v[166:167], v[166:167]
	v_add_f32_e32 v20, v113, v20
	v_add_f32_e32 v20, v196, v20
	v_pk_mul_f32 v[198:199], v[168:169], v[168:169]
	v_add_f32_e32 v20, v197, v20
	s_waitcnt lgkmcnt(0)
	v_add_f32_e32 v182, v6, v5
	ds_bpermute_b32 v5, v174, v4
	v_add_f32_e32 v20, v198, v20
	v_pk_mul_f32 v[200:201], v[104:105], v[104:105]
	v_add_f32_e32 v20, v199, v20
	v_add_f32_e32 v20, v200, v20
	v_pk_mul_f32 v[202:203], v[102:103], v[102:103]
	v_add_f32_e32 v20, v201, v20
	v_add_f32_e32 v20, v202, v20
	s_waitcnt lgkmcnt(0)
	v_add_f32_e32 v180, v4, v5
	global_load_dwordx4 v[12:15], v[54:55], off
	global_load_dwordx4 v[4:7], v[54:55], off offset:16
	global_load_dwordx4 v[16:19], v[56:57], off
	global_load_dwordx4 v[8:11], v[56:57], off offset:16
	v_pk_mul_f32 v[100:101], v[110:111], v[110:111]
	v_add_f32_e32 v20, v203, v20
	v_add_f32_e32 v20, v100, v20
	v_pk_mul_f32 v[98:99], v[106:107], v[106:107]
	v_add_f32_e32 v20, v101, v20
	v_add_f32_e32 v20, v98, v20
	v_pk_mul_f32 v[218:219], v[96:97], v[96:97]
	v_add_f32_e32 v20, v99, v20
	v_add_f32_e32 v20, v218, v20
	v_pk_mul_f32 v[220:221], v[94:95], v[94:95]
	v_add_f32_e32 v20, v219, v20
	v_add_f32_e32 v20, v220, v20
	v_pk_mul_f32 v[222:223], v[92:93], v[92:93]
	v_add_f32_e32 v20, v221, v20
	v_add_f32_e32 v20, v222, v20
	v_pk_mul_f32 v[224:225], v[90:91], v[90:91]
	v_add_f32_e32 v20, v223, v20
	v_add_f32_e32 v20, v224, v20
	v_add_f32_e32 v20, v225, v20
	ds_bpermute_b32 v21, v53, v20
	ds_bpermute_b32 v185, v175, v184
	ds_bpermute_b32 v183, v175, v182
	ds_bpermute_b32 v181, v175, v180
	s_waitcnt lgkmcnt(3)
	v_add_f32_e32 v20, v20, v21
	ds_bpermute_b32 v21, v171, v20
	s_waitcnt lgkmcnt(0)
	v_add_f32_e32 v20, v20, v21
	ds_bpermute_b32 v21, v172, v20
	s_waitcnt lgkmcnt(0)
	v_add_f32_e32 v20, v20, v21
	ds_bpermute_b32 v21, v173, v20
	s_waitcnt lgkmcnt(0)
	v_add_f32_e32 v20, v20, v21
	ds_bpermute_b32 v21, v174, v20
	s_waitcnt lgkmcnt(0)
	v_add_f32_e32 v20, v20, v21
	ds_bpermute_b32 v21, v175, v20
	s_waitcnt lgkmcnt(0)
	v_add_f32_e32 v20, v20, v21
	v_fmamk_f32 v20, v20, 0x3a000000, v206
	v_cmp_gt_f32_e32 vcc, s48, v20
	v_mul_f32_e32 v21, 0x4f800000, v20
	s_nop 0
	v_cndmask_b32_e32 v20, v20, v21, vcc
	v_sqrt_f32_e32 v21, v20
	s_nop 0
	v_add_u32_e32 v98, -1, v21
	v_fma_f32 v99, -v98, v21, v20
	v_cmp_ge_f32_e64 s[42:43], 0, v99
	v_add_u32_e32 v99, 1, v21
	s_nop 0
	v_cndmask_b32_e64 v98, v21, v98, s[42:43]
	v_fma_f32 v21, -v99, v21, v20
	v_cmp_lt_f32_e64 s[42:43], 0, v21
	s_nop 1
	v_cndmask_b32_e64 v21, v98, v99, s[42:43]
	v_mul_f32_e32 v98, 0x37800000, v21
	v_cndmask_b32_e32 v21, v21, v98, vcc
	v_cmp_class_f32_e32 vcc, v20, v205
	s_nop 1
	v_cndmask_b32_e32 v20, v21, v20, vcc
	v_div_scale_f32 v21, s[14:15], v20, v20, 1.0
	v_rcp_f32_e32 v98, v21
	s_nop 0
	v_fma_f32 v99, -v21, v98, 1.0
	v_fmac_f32_e32 v98, v99, v98
	v_div_scale_f32 v99, vcc, 1.0, v20, 1.0
	v_mul_f32_e32 v100, v99, v98
	v_fma_f32 v101, -v21, v100, v99
	v_fmac_f32_e32 v100, v101, v98
	v_fma_f32 v21, -v21, v100, v99
	v_div_fmas_f32 v21, v21, v98, v100
	v_div_fixup_f32 v100, v21, v20, 1.0
	v_pk_mul_f32 v[0:1], v[0:1], v[100:101] op_sel_hi:[1,0]
	s_waitcnt vmcnt(1)
	v_pk_fma_f32 v[20:21], v[12:13], v[0:1], v[16:17]
	v_pk_mul_f32 v[0:1], v[2:3], v[100:101] op_sel_hi:[1,0]
	v_pk_mul_f32 v[2:3], v[22:23], v[100:101] op_sel_hi:[1,0]
	s_waitcnt vmcnt(0)
	global_load_dwordx4 v[228:231], v[54:55], off offset:2064
	s_nop 0
	global_load_dwordx4 v[232:235], v[54:55], off offset:2048
	global_load_dwordx4 v[240:243], v[56:57], off offset:2048
	global_load_dwordx4 v[236:239], v[56:57], off offset:2064
	v_pk_fma_f32 v[0:1], v[4:5], v[0:1], v[8:9]
	v_pk_fma_f32 v[22:23], v[14:15], v[2:3], v[18:19]
	v_pk_mul_f32 v[2:3], v[192:193], v[100:101] op_sel_hi:[1,0]
	s_nop 0
	v_pk_fma_f32 v[2:3], v[6:7], v[2:3], v[10:11]
	s_cbranch_scc1 .LBB0_318
	global_store_dwordx4 v[88:89], v[20:23], off nt
	global_store_dwordx4 v[88:89], v[0:3], off offset:16 nt

.LBB0_332:
	v_mov_b32_e32 v101, v100
	v_pk_mul_f32 v[16:17], v[130:131], v[100:101]
	v_pk_mul_f32 v[18:19], v[166:167], v[100:101]
	v_pk_mul_f32 v[22:23], v[164:165], v[100:101]
	v_pk_mul_f32 v[116:117], v[168:169], v[100:101]
	s_and_b64 vcc, exec, s[44:45]
	s_waitcnt vmcnt(4)
	global_load_dwordx4 v[0:3], v[58:59], off offset:16
	s_nop 0
	global_load_dwordx4 v[4:7], v[58:59], off
	global_load_dwordx4 v[12:15], v[60:61], off
	global_load_dwordx4 v[8:11], v[60:61], off offset:16
	v_pk_fma_f32 v[20:21], v[16:17], v[232:233], v[240:241]
	v_pk_fma_f32 v[16:17], v[18:19], v[228:229], v[236:237]
	v_pk_fma_f32 v[22:23], v[22:23], v[234:235], v[242:243]
	v_pk_fma_f32 v[18:19], v[116:117], v[230:231], v[238:239]
	s_cbranch_vccnz .LBB0_334
	global_store_dwordx4 v[88:89], v[20:23], off offset:2048 nt
	global_store_dwordx4 v[88:89], v[16:19], off offset:2064 nt

.LBB0_336:
	v_mov_b32_e32 v113, v112
	v_pk_mul_f32 v[16:17], v[70:71], v[112:113]
	v_pk_mul_f32 v[18:19], v[74:75], v[112:113]
	v_pk_fma_f32 v[20:21], v[16:17], v[232:233], v[240:241]
	v_pk_fma_f32 v[16:17], v[18:19], v[228:229], v[236:237]
	v_pk_mul_f32 v[18:19], v[68:69], v[112:113]
	v_pk_mul_f32 v[68:69], v[72:73], v[112:113]
	v_pk_fma_f32 v[22:23], v[18:19], v[234:235], v[242:243]
	s_and_b64 vcc, exec, s[44:45]
	v_pk_fma_f32 v[18:19], v[68:69], v[230:231], v[238:239]
	s_cbranch_vccnz .LBB0_338
	v_add_co_u32_e32 v68, vcc, 0x2000000, v88
	s_nop 1
	v_addc_co_u32_e32 v69, vcc, 0, v89, vcc
	global_store_dwordx4 v[68:69], v[20:23], off offset:2048 nt
	global_store_dwordx4 v[68:69], v[16:19], off offset:2064 nt

.LBB0_340:
	v_mov_b32_e32 v109, v108
	v_pk_mul_f32 v[16:17], v[122:123], v[108:109]
	v_pk_mul_f32 v[18:19], v[126:127], v[108:109]
	v_pk_fma_f32 v[20:21], v[16:17], v[232:233], v[240:241]
	v_pk_fma_f32 v[16:17], v[18:19], v[228:229], v[236:237]
	v_pk_mul_f32 v[18:19], v[118:119], v[108:109]
	v_pk_mul_f32 v[68:69], v[124:125], v[108:109]
	v_pk_fma_f32 v[22:23], v[18:19], v[234:235], v[242:243]
	s_and_b64 vcc, exec, s[44:45]
	v_pk_fma_f32 v[18:19], v[68:69], v[230:231], v[238:239]
	s_cbranch_vccnz .LBB0_342
	v_add_co_u32_e32 v68, vcc, 0x4000000, v88
	s_nop 1
	v_addc_co_u32_e32 v69, vcc, 0, v89, vcc
	global_store_dwordx4 v[68:69], v[20:23], off offset:2048 nt
	global_store_dwordx4 v[68:69], v[16:19], off offset:2064 nt

.LBB0_344:
	v_mov_b32_e32 v115, v114
	v_pk_mul_f32 v[16:17], v[150:151], v[114:115]
	v_pk_mul_f32 v[18:19], v[154:155], v[114:115]
	v_pk_fma_f32 v[232:233], v[16:17], v[232:233], v[240:241]
	v_pk_fma_f32 v[228:229], v[18:19], v[228:229], v[236:237]
	v_pk_mul_f32 v[236:237], v[148:149], v[114:115]
	v_pk_mul_f32 v[240:241], v[152:153], v[114:115]
	v_pk_fma_f32 v[234:235], v[236:237], v[234:235], v[242:243]
	s_and_b64 vcc, exec, s[44:45]
	v_pk_fma_f32 v[230:231], v[240:241], v[230:231], v[238:239]
	s_cbranch_vccnz .LBB0_346
	v_add_co_u32_e32 v236, vcc, 0x6000000, v88
	s_nop 1
	v_addc_co_u32_e32 v237, vcc, 0, v89, vcc
	global_store_dwordx4 v[236:237], v[232:235], off offset:2048 nt
	global_store_dwordx4 v[236:237], v[228:231], off offset:2064 nt
.LBB0_346:
	s_and_b64 vcc, exec, s[42:43]
	s_cbranch_vccnz .LBB0_348
	v_cvt_pk_bf16_f32 v232, v232, v233
	v_cvt_pk_bf16_f32 v233, v234, v235
	v_cvt_pk_bf16_f32 v234, v228, v229
	v_add_co_u32_e32 v228, vcc, 0x3000000, v98
	v_cvt_pk_bf16_f32 v235, v230, v231
	s_nop 0
	v_addc_co_u32_e32 v229, vcc, 0, v99, vcc
	flat_store_dwordx4 v[228:229], v[232:235] offset:1024
.LBB0_348:
	v_pk_mul_f32 v[16:17], v[104:105], v[100:101]
	v_pk_mul_f32 v[18:19], v[110:111], v[100:101]
	v_pk_mul_f32 v[22:23], v[102:103], v[100:101]
	v_pk_mul_f32 v[68:69], v[106:107], v[100:101]
	s_and_b64 vcc, exec, s[44:45]
	s_waitcnt vmcnt(4)
	global_load_dwordx4 v[228:231], v[62:63], off offset:16
	s_nop 0
	global_load_dwordx4 v[232:235], v[62:63], off
	global_load_dwordx4 v[240:243], v[64:65], off
	global_load_dwordx4 v[236:239], v[64:65], off offset:16
	v_pk_fma_f32 v[20:21], v[16:17], v[4:5], v[12:13]
	v_pk_fma_f32 v[16:17], v[18:19], v[0:1], v[8:9]
	v_pk_fma_f32 v[22:23], v[22:23], v[6:7], v[14:15]
	v_pk_fma_f32 v[18:19], v[68:69], v[2:3], v[10:11]
	s_cbranch_vccnz .LBB0_350
	v_add_co_u32_e32 v68, vcc, 0x1000, v88
	s_nop 1
	v_addc_co_u32_e32 v69, vcc, 0, v89, vcc
	global_store_dwordx4 v[68:69], v[20:23], off nt
	global_store_dwordx4 v[68:69], v[16:19], off offset:16 nt

.LBB0_364:
	v_pk_mul_f32 v[16:17], v[96:97], v[100:101]
	v_pk_mul_f32 v[18:19], v[92:93], v[100:101]
	v_pk_mul_f32 v[22:23], v[94:95], v[100:101]
	v_pk_mul_f32 v[32:33], v[90:91], v[100:101]
	s_and_b64 vcc, exec, s[44:45]
	s_waitcnt vmcnt(4)
	v_pk_fma_f32 v[20:21], v[16:17], v[232:233], v[240:241]
	v_pk_fma_f32 v[16:17], v[18:19], v[228:229], v[236:237]
	v_pk_fma_f32 v[22:23], v[22:23], v[234:235], v[242:243]
	v_pk_fma_f32 v[18:19], v[32:33], v[230:231], v[238:239]
	s_cbranch_vccnz .LBB0_366
	v_add_co_u32_e32 v32, vcc, 0x1000, v88
	s_nop 1
	v_addc_co_u32_e32 v33, vcc, 0, v89, vcc
	global_store_dwordx4 v[32:33], v[20:23], off offset:2048 nt
	global_store_dwordx4 v[32:33], v[16:19], off offset:2064 nt

.LBB0_368:
	v_pk_mul_f32 v[16:17], v[38:39], v[112:113]
	v_pk_mul_f32 v[18:19], v[42:43], v[112:113]
	v_pk_fma_f32 v[20:21], v[16:17], v[232:233], v[240:241]
	v_pk_fma_f32 v[16:17], v[18:19], v[228:229], v[236:237]
	v_pk_mul_f32 v[18:19], v[36:37], v[112:113]
	v_pk_mul_f32 v[32:33], v[40:41], v[112:113]
	v_pk_fma_f32 v[22:23], v[18:19], v[234:235], v[242:243]
	s_and_b64 vcc, exec, s[44:45]
	v_pk_fma_f32 v[18:19], v[32:33], v[230:231], v[238:239]
	s_cbranch_vccnz .LBB0_370
	v_add_co_u32_e32 v32, vcc, 0x2001000, v88
	s_nop 1
	v_addc_co_u32_e32 v33, vcc, 0, v89, vcc
	global_store_dwordx4 v[32:33], v[20:23], off offset:2048 nt
	global_store_dwordx4 v[32:33], v[16:19], off offset:2064 nt

.LBB0_372:
	v_pk_mul_f32 v[16:17], v[26:27], v[108:109]
	v_pk_mul_f32 v[18:19], v[30:31], v[108:109]
	v_pk_fma_f32 v[20:21], v[16:17], v[232:233], v[240:241]
	v_pk_fma_f32 v[16:17], v[18:19], v[228:229], v[236:237]
	v_pk_mul_f32 v[18:19], v[24:25], v[108:109]
	v_pk_mul_f32 v[24:25], v[28:29], v[108:109]
	v_pk_fma_f32 v[22:23], v[18:19], v[234:235], v[242:243]
	s_and_b64 vcc, exec, s[44:45]
	v_pk_fma_f32 v[18:19], v[24:25], v[230:231], v[238:239]
	s_cbranch_vccnz .LBB0_374
	v_add_co_u32_e32 v24, vcc, 0x4001000, v88
	s_nop 1
	v_addc_co_u32_e32 v25, vcc, 0, v89, vcc
	global_store_dwordx4 v[24:25], v[20:23], off offset:2048 nt
	global_store_dwordx4 v[24:25], v[16:19], off offset:2064 nt

.LBB0_376:
	v_pk_mul_f32 v[16:17], v[82:83], v[114:115]
	v_pk_mul_f32 v[18:19], v[86:87], v[114:115]
	v_pk_fma_f32 v[232:233], v[16:17], v[232:233], v[240:241]
	v_pk_fma_f32 v[228:229], v[18:19], v[228:229], v[236:237]
	v_pk_mul_f32 v[236:237], v[80:81], v[114:115]
	v_pk_mul_f32 v[240:241], v[84:85], v[114:115]
	v_pk_fma_f32 v[234:235], v[236:237], v[234:235], v[242:243]
	s_and_b64 vcc, exec, s[44:45]
	v_pk_fma_f32 v[230:231], v[240:241], v[230:231], v[238:239]
	s_cbranch_vccnz .LBB0_378
	v_add_co_u32_e32 v236, vcc, 0x6001000, v88
	s_nop 1
	v_addc_co_u32_e32 v237, vcc, 0, v89, vcc
	global_store_dwordx4 v[236:237], v[232:235], off offset:2048 nt
	global_store_dwordx4 v[236:237], v[228:231], off offset:2064 nt
.LBB0_378:
	s_and_b64 vcc, exec, s[42:43]
	s_cbranch_vccnz .LBB0_315
	v_cvt_pk_bf16_f32 v232, v232, v233
	v_cvt_pk_bf16_f32 v233, v234, v235
	v_cvt_pk_bf16_f32 v234, v228, v229
	v_add_co_u32_e32 v228, vcc, 0x3000000, v98
	v_cvt_pk_bf16_f32 v235, v230, v231
	s_nop 0
	v_addc_co_u32_e32 v229, vcc, 0, v99, vcc
	flat_store_dwordx4 v[228:229], v[232:235] offset:3072
	s_branch .LBB0_315
